# phase 0 W_out transpose tile: all 16 weight loads issued back to back with counted waits instead of two batches of eight
# speedup vs baseline: 1.0059x; 1.0024x over previous
; DI bf16_t f2bf(float a) { return (bf16_t)(pk2(a, 0.f) & 0xffffu); }
; template <int MODE>
; DI void transpose_tile(const float* __restrict__ W, int K, int Nsrc, bf16_t* __restrict__ WT, int ldo, const float* __restrict__ gain, int k0, int n0,
;                        unsigned char* smem, int tid) {
;     ...
; #pragma unroll 4
;     for (int i = 0; i < 16; ++i) {
;         const int e = tid + 256 * i, kk = e >> 6, nn = e & 63;
;         const int src = MODE == 0 ? win_src_col(n0 + nn) : (n0 + nn);
;         float v = src >= 0 ? W[(size_t)(k0 + kk) * Nsrc + src] : 0.f;
;         if (gain) v *= gain[k0 + kk];
;         t[nn * 66 + kk] = f2bf(v);
;     }
;     __syncthreads();
; #pragma unroll
;     for (int i = 0; i < 2; ++i) {
;         const int c = tid + 256 * i, nn = c >> 3, kc = c & 7;
;         const unsigned* s = (const unsigned*)(t + nn * 66 + kc * 8);
;         u32x4 o = {s[0], s[1], s[2], s[3]};
;         *(u32x4*)(WT + (size_t)(n0 + nn) * ldo + k0 + kc * 8) = o;
;     }
;     __syncthreads();
; DI void phase0(const Params& p, unsigned char* smem) {
;     ...
;         transpose_tile<1>(p.w_out, 2048, 2048, (bf16_t*)(p.ws + WS_WOUT), LDK, nullptr, (r / 32) * 64, (r % 32) * 64, smem, tid);
.LBB0_30:
	s_cmpk_gt_u32 s35, 0xcbf
	s_cbranch_scc0 .LBB0_48
	s_lshl_b32 s0, s35, 6
	s_lshl_b32 s5, s35, 1
	s_and_b32 s4, s0, 0x7c0
	s_cmpk_gt_u32 s35, 0xd3f
	s_mov_b64 s[0:1], -1
	s_cbranch_scc0 .LBB0_35
	v_and_b32_e32 v1, 63, v6
	v_or_b32_e32 v3, s4, v1
	s_add_i32 s0, s5, 0x7fffe580
	v_lshlrev_b32_e32 v4, 2, v3
	s_and_b32 s0, s0, 0x7fffffc0
	v_lshl_add_u64 v[8:9], s[68:69], 0, v[4:5]
	v_mov_b32_e32 v3, s10
	v_add_u32_e32 v4, 0x200, v6
	v_add_u32_e32 v10, 0x400, v6
	v_add_u32_e32 v12, 0x600, v6
	v_mad_u32_u24 v13, v1, s27, v3
	v_lshrrev_b32_e32 v3, 6, v6
	v_add_u32_e32 v10, s0, v3
	v_ashrrev_i32_e32 v11, 31, v10
	v_lshlrev_b64 v[10:11], 13, v[10:11]
	v_lshl_add_u64 v[10:11], v[8:9], 0, v[10:11]
	v_lshl_add_u32 v13, v3, 1, v13
	s_mov_b32 s6, 0x8000
	s_mov_b32 s7, 0
	global_load_dword v14, v[10:11], off
	v_lshl_add_u64 v[10:11], v[10:11], 0, s[6:7]
	global_load_dword v15, v[10:11], off
	v_lshl_add_u64 v[10:11], v[10:11], 0, s[6:7]
	global_load_dword v16, v[10:11], off
	v_lshl_add_u64 v[10:11], v[10:11], 0, s[6:7]
	global_load_dword v17, v[10:11], off
	v_lshl_add_u64 v[10:11], v[10:11], 0, s[6:7]
	global_load_dword v18, v[10:11], off
	v_lshl_add_u64 v[10:11], v[10:11], 0, s[6:7]
	global_load_dword v19, v[10:11], off
	v_lshl_add_u64 v[10:11], v[10:11], 0, s[6:7]
	global_load_dword v20, v[10:11], off
	v_lshl_add_u64 v[10:11], v[10:11], 0, s[6:7]
	global_load_dword v21, v[10:11], off
	v_lshl_add_u64 v[10:11], v[10:11], 0, s[6:7]
	global_load_dword v22, v[10:11], off
	v_lshl_add_u64 v[10:11], v[10:11], 0, s[6:7]
	global_load_dword v23, v[10:11], off
	v_lshl_add_u64 v[10:11], v[10:11], 0, s[6:7]
	global_load_dword v24, v[10:11], off
	v_lshl_add_u64 v[10:11], v[10:11], 0, s[6:7]
	global_load_dword v25, v[10:11], off
	v_lshl_add_u64 v[10:11], v[10:11], 0, s[6:7]
	global_load_dword v26, v[10:11], off
	v_lshl_add_u64 v[10:11], v[10:11], 0, s[6:7]
	global_load_dword v27, v[10:11], off
	v_lshl_add_u64 v[10:11], v[10:11], 0, s[6:7]
	global_load_dword v28, v[10:11], off
	v_lshl_add_u64 v[10:11], v[10:11], 0, s[6:7]
	global_load_dword v29, v[10:11], off
	s_waitcnt vmcnt(14)
	v_cvt_pk_bf16_f32 v14, v14, v15
	ds_write_b16 v13, v14
	ds_write_b16_d16_hi v13, v14 offset:8
	s_waitcnt vmcnt(12)
	v_cvt_pk_bf16_f32 v16, v16, v17
	ds_write_b16 v13, v16 offset:16
	ds_write_b16_d16_hi v13, v16 offset:24
	s_waitcnt vmcnt(10)
	v_cvt_pk_bf16_f32 v18, v18, v19
	ds_write_b16 v13, v18 offset:32
	ds_write_b16_d16_hi v13, v18 offset:40
	s_waitcnt vmcnt(8)
	v_cvt_pk_bf16_f32 v20, v20, v21
	ds_write_b16 v13, v20 offset:48
	ds_write_b16_d16_hi v13, v20 offset:56
	s_waitcnt vmcnt(6)
	v_cvt_pk_bf16_f32 v22, v22, v23
	ds_write_b16 v13, v22 offset:64
	ds_write_b16_d16_hi v13, v22 offset:72
	s_waitcnt vmcnt(4)
	v_cvt_pk_bf16_f32 v24, v24, v25
	ds_write_b16 v13, v24 offset:80
	ds_write_b16_d16_hi v13, v24 offset:88
	s_waitcnt vmcnt(2)
	v_cvt_pk_bf16_f32 v26, v26, v27
	ds_write_b16 v13, v26 offset:96
	ds_write_b16_d16_hi v13, v26 offset:104
	s_waitcnt vmcnt(0)
	v_cvt_pk_bf16_f32 v28, v28, v29
	ds_write_b16 v13, v28 offset:112
	ds_write_b16_d16_hi v13, v28 offset:120
	v_lshlrev_b32_e32 v1, 4, v6
	s_lshl_b32 s0, s0, 1
	v_and_b32_e32 v4, 0x70, v1
	s_add_u32 s0, s3, s0
	v_add_u32_e32 v12, s10, v4
	s_addc_u32 s1, s11, 0
	v_ashrrev_i32_e32 v1, 3, v6
	v_lshl_add_u64 v[16:17], s[0:1], 0, v[4:5]
	v_mad_u64_u32 v[10:11], s[0:1], v1, s27, v[12:13]
	v_add_u32_e32 v1, s4, v1
	v_mad_i64_i32 v[18:19], s[0:1], v1, s28, v[16:17]
	v_add_u32_e32 v1, 0x100, v6
	v_ashrrev_i32_e32 v1, 3, v1
	s_waitcnt lgkmcnt(0)
	s_barrier
	ds_read2_b32 v[8:9], v10 offset1:1
	ds_read2_b32 v[10:11], v10 offset0:2 offset1:3
	v_mad_u64_u32 v[14:15], s[0:1], v1, s27, v[12:13]
	ds_read2_b32 v[12:13], v14 offset1:1
	ds_read2_b32 v[14:15], v14 offset0:2 offset1:3
	v_add_u32_e32 v1, s4, v1
	s_waitcnt lgkmcnt(2)
	global_store_dwordx4 v[18:19], v[8:11], off
	s_nop 1
	v_mad_i64_i32 v[8:9], s[0:1], v1, s28, v[16:17]
	s_waitcnt lgkmcnt(0)
	global_store_dwordx4 v[8:9], v[12:15], off
	s_barrier
	s_mov_b64 s[0:1], 0
